# speedup vs baseline: 1.1237x; 1.0049x over previous
; DI unsigned pack2(float a, float b) { return (unsigned)f2bf(a) | ((unsigned)f2bf(b) << 16); }
; DI float bflo(unsigned w) { return __uint_as_float(w << 16); }
; DI float bfhi(unsigned w) { return __uint_as_float(w & 0xffff0000u); }
;   DI void operator()(f32x4 (&acc)[4][4], int m0w, int n0w, int fr, int fq) const {
; #pragma unroll
;     for (int mi = 0; mi < 4; ++mi)
; #pragma unroll
;       for (int ni = 0; ni < 4; ++ni) {
;         const size_t o = (size_t)(m0w + mi * 16 + fr) * D + n0w + ni * 16 + fq * 4;
;         const uint2 gw = *(const uint2*)(G + o);
;         f32x4 m;
;         m[0] = bflo(gw.x) * acc[mi][ni][0]; m[1] = bfhi(gw.x) * acc[mi][ni][1];
;         m[2] = bflo(gw.y) * acc[mi][ni][2]; m[3] = bfhi(gw.y) * acc[mi][ni][3];
;         if (b > 0) m += *(const f32x4*)(MACC + o);
;         if (b < 2) *(f32x4*)(MACC + o) = m;
;         else { uint2 w; w.x = pack2(m[0], m[1]); w.y = pack2(m[2], m[3]); *(uint2*)(MERGED + o) = w; }
;       }
;   }
.LBB0_464:
	v_add_u32_e32 v136, s2, v155
	v_or_b32_e32 v133, s3, v145
	v_readlane_b32 s0, v248, 7
	v_readlane_b32 s1, v248, 8
	v_ashrrev_i32_e32 v135, 31, v133
	v_or_b32_e32 v134, v133, v132
	v_readlane_b32 s40, v246, 1
	v_readlane_b32 s41, v246, 2
	v_readlane_b32 s42, v246, 3
	v_readlane_b32 s43, v246, 4
	v_readlane_b32 s44, v246, 5
	v_readlane_b32 s45, v246, 6
	v_readlane_b32 s46, v246, 7
	v_readlane_b32 s47, v246, 8
	v_readlane_b32 s2, v248, 3
	v_readlane_b32 s3, v248, 4
	s_nop 1
	s_sub_u32 s2, s2, s0
	s_subb_u32 s3, s3, s1
	v_mov_b32_e32 v138, v136
	v_ashrrev_i32_e32 v139, 31, v138
	v_lshlrev_b64 v[138:139], 11, v[138:139]
	v_lshl_add_u64 v[138:139], v[138:139], 0, v[134:135]
	v_lshl_add_u64 v[140:141], v[138:139], 1, s[0:1]
	v_lshl_add_u64 v[150:151], v[138:139], 2, s[42:43]
	global_load_dwordx2 v[156:157], v[140:141], off
	global_load_dwordx2 v[158:159], v[140:141], off offset:32
	global_load_dwordx2 v[160:161], v[140:141], off offset:64
	global_load_dwordx2 v[162:163], v[140:141], off offset:96
	v_or_b32_e32 v138, 16, v136
	v_ashrrev_i32_e32 v139, 31, v138
	v_lshlrev_b64 v[138:139], 11, v[138:139]
	v_lshl_add_u64 v[138:139], v[138:139], 0, v[134:135]
	v_lshl_add_u64 v[142:143], v[138:139], 1, s[0:1]
	v_lshl_add_u64 v[152:153], v[138:139], 2, s[42:43]
	global_load_dwordx2 v[164:165], v[142:143], off
	global_load_dwordx2 v[166:167], v[142:143], off offset:32
	global_load_dwordx2 v[168:169], v[142:143], off offset:64
	global_load_dwordx2 v[170:171], v[142:143], off offset:96
	v_or_b32_e32 v138, 32, v136
	v_ashrrev_i32_e32 v139, 31, v138
	v_lshlrev_b64 v[138:139], 11, v[138:139]
	v_lshl_add_u64 v[138:139], v[138:139], 0, v[134:135]
	v_lshl_add_u64 v[146:147], v[138:139], 1, s[0:1]
	v_lshl_add_u64 v[236:237], v[138:139], 2, s[42:43]
	global_load_dwordx2 v[172:173], v[146:147], off
	global_load_dwordx2 v[174:175], v[146:147], off offset:32
	global_load_dwordx2 v[176:177], v[146:147], off offset:64
	global_load_dwordx2 v[178:179], v[146:147], off offset:96
	v_or_b32_e32 v138, 48, v136
	v_ashrrev_i32_e32 v139, 31, v138
	v_lshlrev_b64 v[138:139], 11, v[138:139]
	v_lshl_add_u64 v[138:139], v[138:139], 0, v[134:135]
	v_lshl_add_u64 v[148:149], v[138:139], 1, s[0:1]
	v_lshl_add_u64 v[238:239], v[138:139], 2, s[42:43]
	global_load_dwordx2 v[180:181], v[148:149], off
	global_load_dwordx2 v[182:183], v[148:149], off offset:32
	global_load_dwordx2 v[226:227], v[148:149], off offset:64
	global_load_dwordx2 v[228:229], v[148:149], off offset:96
	s_and_b64 vcc, exec, s[22:23]
	s_cbranch_vccz .Lem_n
	s_and_b64 vcc, exec, s[24:25]
	s_cbranch_vccz .Lem_lp
	global_load_dwordx4 v[186:189], v[150:151], off
	global_load_dwordx4 v[190:193], v[150:151], off offset:64
	global_load_dwordx4 v[194:197], v[150:151], off offset:128
	global_load_dwordx4 v[198:201], v[150:151], off offset:192
	global_load_dwordx4 v[202:205], v[152:153], off
	global_load_dwordx4 v[206:209], v[152:153], off offset:64
	global_load_dwordx4 v[210:213], v[152:153], off offset:128
	global_load_dwordx4 v[230:233], v[152:153], off offset:192
	s_waitcnt vmcnt(7)
	v_lshlrev_b32_e32 v244, 16, v156
	v_and_b32_e32 v245, 0xffff0000, v156
	v_lshlrev_b32_e32 v156, 16, v157
	v_and_b32_e32 v157, 0xffff0000, v157
	v_pk_mul_f32 v[126:127], v[126:127], v[156:157]
	v_pk_mul_f32 v[124:125], v[124:125], v[244:245]
	v_pk_add_f32 v[126:127], v[126:127], v[188:189]
	v_pk_add_f32 v[124:125], v[124:125], v[186:187]
	global_store_dwordx4 v[150:151], v[124:127], off
	global_load_dwordx4 v[186:189], v[236:237], off
	s_waitcnt vmcnt(8)
	v_lshlrev_b32_e32 v244, 16, v158
	v_and_b32_e32 v245, 0xffff0000, v158
	v_lshlrev_b32_e32 v158, 16, v159
	v_and_b32_e32 v159, 0xffff0000, v159
	v_pk_mul_f32 v[122:123], v[122:123], v[158:159]
	v_pk_mul_f32 v[120:121], v[120:121], v[244:245]
	v_pk_add_f32 v[122:123], v[122:123], v[192:193]
	v_pk_add_f32 v[120:121], v[120:121], v[190:191]
	global_store_dwordx4 v[150:151], v[120:123], off offset:64
	global_load_dwordx4 v[190:193], v[236:237], off offset:64
	s_waitcnt vmcnt(9)
	v_lshlrev_b32_e32 v244, 16, v160
	v_and_b32_e32 v245, 0xffff0000, v160
	v_lshlrev_b32_e32 v160, 16, v161
	v_and_b32_e32 v161, 0xffff0000, v161
	v_pk_mul_f32 v[118:119], v[118:119], v[160:161]
	v_pk_mul_f32 v[116:117], v[116:117], v[244:245]
	v_pk_add_f32 v[118:119], v[118:119], v[196:197]
	v_pk_add_f32 v[116:117], v[116:117], v[194:195]
	global_store_dwordx4 v[150:151], v[116:119], off offset:128
	global_load_dwordx4 v[194:197], v[236:237], off offset:128
	s_waitcnt vmcnt(10)
	v_lshlrev_b32_e32 v244, 16, v162
	v_and_b32_e32 v245, 0xffff0000, v162
	v_lshlrev_b32_e32 v162, 16, v163
	v_and_b32_e32 v163, 0xffff0000, v163
	v_pk_mul_f32 v[114:115], v[114:115], v[162:163]
	v_pk_mul_f32 v[112:113], v[112:113], v[244:245]
	v_pk_add_f32 v[114:115], v[114:115], v[200:201]
	v_pk_add_f32 v[112:113], v[112:113], v[198:199]
	global_store_dwordx4 v[150:151], v[112:115], off offset:192
	global_load_dwordx4 v[198:201], v[236:237], off offset:192
	s_waitcnt vmcnt(11)
	v_lshlrev_b32_e32 v244, 16, v164
	v_and_b32_e32 v245, 0xffff0000, v164
	v_lshlrev_b32_e32 v164, 16, v165
	v_and_b32_e32 v165, 0xffff0000, v165
	v_pk_mul_f32 v[110:111], v[110:111], v[164:165]
	v_pk_mul_f32 v[108:109], v[108:109], v[244:245]
	v_pk_add_f32 v[110:111], v[110:111], v[204:205]
	v_pk_add_f32 v[108:109], v[108:109], v[202:203]
	global_store_dwordx4 v[152:153], v[108:111], off
	global_load_dwordx4 v[202:205], v[238:239], off
	s_waitcnt vmcnt(12)
; DI unsigned pack2(float a, float b) { return (unsigned)f2bf(a) | ((unsigned)f2bf(b) << 16); }
; DI float bflo(unsigned w) { return __uint_as_float(w << 16); }
; DI float bfhi(unsigned w) { return __uint_as_float(w & 0xffff0000u); }
;   DI void operator()(f32x4 (&acc)[4][4], int m0w, int n0w, int fr, int fq) const {
; #pragma unroll
;     for (int mi = 0; mi < 4; ++mi)
; #pragma unroll
;       for (int ni = 0; ni < 4; ++ni) {
;         const size_t o = (size_t)(m0w + mi * 16 + fr) * D + n0w + ni * 16 + fq * 4;
;         const uint2 gw = *(const uint2*)(G + o);
;         f32x4 m;
;         m[0] = bflo(gw.x) * acc[mi][ni][0]; m[1] = bfhi(gw.x) * acc[mi][ni][1];
;         m[2] = bflo(gw.y) * acc[mi][ni][2]; m[3] = bfhi(gw.y) * acc[mi][ni][3];
;         if (b > 0) m += *(const f32x4*)(MACC + o);
;         if (b < 2) *(f32x4*)(MACC + o) = m;
;         else { uint2 w; w.x = pack2(m[0], m[1]); w.y = pack2(m[2], m[3]); *(uint2*)(MERGED + o) = w; }
;       }
;   }
	v_lshlrev_b32_e32 v244, 16, v166
	v_and_b32_e32 v245, 0xffff0000, v166
	v_lshlrev_b32_e32 v166, 16, v167
	v_and_b32_e32 v167, 0xffff0000, v167
	v_pk_mul_f32 v[106:107], v[106:107], v[166:167]
	v_pk_mul_f32 v[104:105], v[104:105], v[244:245]
	v_pk_add_f32 v[106:107], v[106:107], v[208:209]
	v_pk_add_f32 v[104:105], v[104:105], v[206:207]
	global_store_dwordx4 v[152:153], v[104:107], off offset:64
	global_load_dwordx4 v[206:209], v[238:239], off offset:64
	s_waitcnt vmcnt(13)
	v_lshlrev_b32_e32 v244, 16, v168
	v_and_b32_e32 v245, 0xffff0000, v168
	v_lshlrev_b32_e32 v168, 16, v169
	v_and_b32_e32 v169, 0xffff0000, v169
	v_pk_mul_f32 v[102:103], v[102:103], v[168:169]
	v_pk_mul_f32 v[100:101], v[100:101], v[244:245]
	v_pk_add_f32 v[102:103], v[102:103], v[212:213]
	v_pk_add_f32 v[100:101], v[100:101], v[210:211]
	global_store_dwordx4 v[152:153], v[100:103], off offset:128
	global_load_dwordx4 v[210:213], v[238:239], off offset:128
	s_waitcnt vmcnt(14)
	v_lshlrev_b32_e32 v244, 16, v170
	v_and_b32_e32 v245, 0xffff0000, v170
	v_lshlrev_b32_e32 v170, 16, v171
	v_and_b32_e32 v171, 0xffff0000, v171
	v_pk_mul_f32 v[98:99], v[98:99], v[170:171]
	v_pk_mul_f32 v[96:97], v[96:97], v[244:245]
	v_pk_add_f32 v[98:99], v[98:99], v[232:233]
	v_pk_add_f32 v[96:97], v[96:97], v[230:231]
	global_store_dwordx4 v[152:153], v[96:99], off offset:192
	global_load_dwordx4 v[230:233], v[238:239], off offset:192
	s_waitcnt vmcnt(14)
	v_lshlrev_b32_e32 v244, 16, v172
	v_and_b32_e32 v245, 0xffff0000, v172
	v_lshlrev_b32_e32 v172, 16, v173
	v_and_b32_e32 v173, 0xffff0000, v173
	v_pk_mul_f32 v[94:95], v[94:95], v[172:173]
	v_pk_mul_f32 v[92:93], v[92:93], v[244:245]
	v_pk_add_f32 v[94:95], v[94:95], v[188:189]
	v_pk_add_f32 v[92:93], v[92:93], v[186:187]
	global_store_dwordx4 v[236:237], v[92:95], off
	s_waitcnt vmcnt(13)
	v_lshlrev_b32_e32 v244, 16, v174
	v_and_b32_e32 v245, 0xffff0000, v174
	v_lshlrev_b32_e32 v174, 16, v175
	v_and_b32_e32 v175, 0xffff0000, v175
	v_pk_mul_f32 v[90:91], v[90:91], v[174:175]
	v_pk_mul_f32 v[88:89], v[88:89], v[244:245]
	v_pk_add_f32 v[90:91], v[90:91], v[192:193]
	v_pk_add_f32 v[88:89], v[88:89], v[190:191]
	global_store_dwordx4 v[236:237], v[88:91], off offset:64
	s_waitcnt vmcnt(12)
	v_lshlrev_b32_e32 v244, 16, v176
	v_and_b32_e32 v245, 0xffff0000, v176
	v_lshlrev_b32_e32 v176, 16, v177
	v_and_b32_e32 v177, 0xffff0000, v177
	v_pk_mul_f32 v[86:87], v[86:87], v[176:177]
	v_pk_mul_f32 v[84:85], v[84:85], v[244:245]
	v_pk_add_f32 v[86:87], v[86:87], v[196:197]
	v_pk_add_f32 v[84:85], v[84:85], v[194:195]
	global_store_dwordx4 v[236:237], v[84:87], off offset:128
	s_waitcnt vmcnt(11)
	v_lshlrev_b32_e32 v244, 16, v178
	v_and_b32_e32 v245, 0xffff0000, v178
	v_lshlrev_b32_e32 v178, 16, v179
	v_and_b32_e32 v179, 0xffff0000, v179
	v_pk_mul_f32 v[82:83], v[82:83], v[178:179]
	v_pk_mul_f32 v[80:81], v[80:81], v[244:245]
	v_pk_add_f32 v[82:83], v[82:83], v[200:201]
	v_pk_add_f32 v[80:81], v[80:81], v[198:199]
	global_store_dwordx4 v[236:237], v[80:83], off offset:192
	s_waitcnt vmcnt(10)
	v_lshlrev_b32_e32 v244, 16, v180
	v_and_b32_e32 v245, 0xffff0000, v180
	v_lshlrev_b32_e32 v180, 16, v181
	v_and_b32_e32 v181, 0xffff0000, v181
	v_pk_mul_f32 v[78:79], v[78:79], v[180:181]
	v_pk_mul_f32 v[76:77], v[76:77], v[244:245]
	v_pk_add_f32 v[78:79], v[78:79], v[204:205]
	v_pk_add_f32 v[76:77], v[76:77], v[202:203]
	global_store_dwordx4 v[238:239], v[76:79], off
	s_waitcnt vmcnt(9)
	v_lshlrev_b32_e32 v244, 16, v182
	v_and_b32_e32 v245, 0xffff0000, v182
	v_lshlrev_b32_e32 v182, 16, v183
	v_and_b32_e32 v183, 0xffff0000, v183
	v_pk_mul_f32 v[74:75], v[74:75], v[182:183]
	v_pk_mul_f32 v[72:73], v[72:73], v[244:245]
	v_pk_add_f32 v[74:75], v[74:75], v[208:209]
	v_pk_add_f32 v[72:73], v[72:73], v[206:207]
	global_store_dwordx4 v[238:239], v[72:75], off offset:64
	s_waitcnt vmcnt(8)
	v_lshlrev_b32_e32 v244, 16, v226
	v_and_b32_e32 v245, 0xffff0000, v226
	v_lshlrev_b32_e32 v226, 16, v227
	v_and_b32_e32 v227, 0xffff0000, v227
	v_pk_mul_f32 v[70:71], v[70:71], v[226:227]
	v_pk_mul_f32 v[68:69], v[68:69], v[244:245]
	v_pk_add_f32 v[70:71], v[70:71], v[212:213]
	v_pk_add_f32 v[68:69], v[68:69], v[210:211]
	global_store_dwordx4 v[238:239], v[68:71], off offset:128
	s_waitcnt vmcnt(7)
	v_lshlrev_b32_e32 v244, 16, v228
	v_and_b32_e32 v245, 0xffff0000, v228
	v_lshlrev_b32_e32 v228, 16, v229
	v_and_b32_e32 v229, 0xffff0000, v229
	v_pk_mul_f32 v[66:67], v[66:67], v[228:229]
	v_pk_mul_f32 v[64:65], v[64:65], v[244:245]
	v_pk_add_f32 v[66:67], v[66:67], v[232:233]
	v_pk_add_f32 v[64:65], v[64:65], v[230:231]
	global_store_dwordx4 v[238:239], v[64:67], off offset:192
	s_branch .LBB0_450
; DI unsigned pack2(float a, float b) { return (unsigned)f2bf(a) | ((unsigned)f2bf(b) << 16); }
; DI float bflo(unsigned w) { return __uint_as_float(w << 16); }
; DI float bfhi(unsigned w) { return __uint_as_float(w & 0xffff0000u); }
;   DI void operator()(f32x4 (&acc)[4][4], int m0w, int n0w, int fr, int fq) const {
; #pragma unroll
;     for (int mi = 0; mi < 4; ++mi)
; #pragma unroll
;       for (int ni = 0; ni < 4; ++ni) {
;         const size_t o = (size_t)(m0w + mi * 16 + fr) * D + n0w + ni * 16 + fq * 4;
;         const uint2 gw = *(const uint2*)(G + o);
;         f32x4 m;
;         m[0] = bflo(gw.x) * acc[mi][ni][0]; m[1] = bfhi(gw.x) * acc[mi][ni][1];
;         m[2] = bflo(gw.y) * acc[mi][ni][2]; m[3] = bfhi(gw.y) * acc[mi][ni][3];
;         if (b > 0) m += *(const f32x4*)(MACC + o);
;         if (b < 2) *(f32x4*)(MACC + o) = m;
;         else { uint2 w; w.x = pack2(m[0], m[1]); w.y = pack2(m[2], m[3]); *(uint2*)(MERGED + o) = w; }
;       }
;   }
.Lem_lp:
	global_load_dwordx4 v[186:189], v[150:151], off
	global_load_dwordx4 v[190:193], v[150:151], off offset:64
	global_load_dwordx4 v[194:197], v[150:151], off offset:128
	global_load_dwordx4 v[198:201], v[150:151], off offset:192
	global_load_dwordx4 v[202:205], v[152:153], off
	global_load_dwordx4 v[206:209], v[152:153], off offset:64
	global_load_dwordx4 v[210:213], v[152:153], off offset:128
	global_load_dwordx4 v[230:233], v[152:153], off offset:192
	s_waitcnt vmcnt(7)
	v_lshlrev_b32_e32 v244, 16, v156
	v_and_b32_e32 v245, 0xffff0000, v156
	v_lshlrev_b32_e32 v156, 16, v157
	v_and_b32_e32 v157, 0xffff0000, v157
	v_pk_mul_f32 v[126:127], v[126:127], v[156:157]
	v_pk_mul_f32 v[124:125], v[124:125], v[244:245]
	v_pk_add_f32 v[126:127], v[126:127], v[188:189]
	v_pk_add_f32 v[124:125], v[124:125], v[186:187]
	v_lshl_add_u64 v[240:241], v[140:141], 0, s[2:3]
	v_cvt_pk_bf16_f32 v124, v124, v125
	v_cvt_pk_bf16_f32 v125, v126, v127
	global_store_dwordx2 v[240:241], v[124:125], off
	global_load_dwordx4 v[186:189], v[236:237], off
	s_waitcnt vmcnt(8)
	v_lshlrev_b32_e32 v244, 16, v158
	v_and_b32_e32 v245, 0xffff0000, v158
	v_lshlrev_b32_e32 v158, 16, v159
	v_and_b32_e32 v159, 0xffff0000, v159
	v_pk_mul_f32 v[122:123], v[122:123], v[158:159]
	v_pk_mul_f32 v[120:121], v[120:121], v[244:245]
	v_pk_add_f32 v[122:123], v[122:123], v[192:193]
	v_pk_add_f32 v[120:121], v[120:121], v[190:191]
	v_cvt_pk_bf16_f32 v120, v120, v121
	v_cvt_pk_bf16_f32 v121, v122, v123
	global_store_dwordx2 v[240:241], v[120:121], off offset:32
	global_load_dwordx4 v[190:193], v[236:237], off offset:64
	s_waitcnt vmcnt(9)
	v_lshlrev_b32_e32 v244, 16, v160
	v_and_b32_e32 v245, 0xffff0000, v160
	v_lshlrev_b32_e32 v160, 16, v161
	v_and_b32_e32 v161, 0xffff0000, v161
	v_pk_mul_f32 v[118:119], v[118:119], v[160:161]
	v_pk_mul_f32 v[116:117], v[116:117], v[244:245]
	v_pk_add_f32 v[118:119], v[118:119], v[196:197]
	v_pk_add_f32 v[116:117], v[116:117], v[194:195]
	v_cvt_pk_bf16_f32 v116, v116, v117
	v_cvt_pk_bf16_f32 v117, v118, v119
	global_store_dwordx2 v[240:241], v[116:117], off offset:64
	global_load_dwordx4 v[194:197], v[236:237], off offset:128
	s_waitcnt vmcnt(10)
	v_lshlrev_b32_e32 v244, 16, v162
	v_and_b32_e32 v245, 0xffff0000, v162
	v_lshlrev_b32_e32 v162, 16, v163
	v_and_b32_e32 v163, 0xffff0000, v163
	v_pk_mul_f32 v[114:115], v[114:115], v[162:163]
	v_pk_mul_f32 v[112:113], v[112:113], v[244:245]
	v_pk_add_f32 v[114:115], v[114:115], v[200:201]
	v_pk_add_f32 v[112:113], v[112:113], v[198:199]
	v_cvt_pk_bf16_f32 v112, v112, v113
	v_cvt_pk_bf16_f32 v113, v114, v115
	global_store_dwordx2 v[240:241], v[112:113], off offset:96
	global_load_dwordx4 v[198:201], v[236:237], off offset:192
	s_waitcnt vmcnt(11)
	v_lshlrev_b32_e32 v244, 16, v164
	v_and_b32_e32 v245, 0xffff0000, v164
	v_lshlrev_b32_e32 v164, 16, v165
	v_and_b32_e32 v165, 0xffff0000, v165
	v_pk_mul_f32 v[110:111], v[110:111], v[164:165]
	v_pk_mul_f32 v[108:109], v[108:109], v[244:245]
	v_pk_add_f32 v[110:111], v[110:111], v[204:205]
	v_pk_add_f32 v[108:109], v[108:109], v[202:203]
	v_lshl_add_u64 v[242:243], v[142:143], 0, s[2:3]
	v_cvt_pk_bf16_f32 v108, v108, v109
	v_cvt_pk_bf16_f32 v109, v110, v111
	global_store_dwordx2 v[242:243], v[108:109], off
	global_load_dwordx4 v[202:205], v[238:239], off
	s_waitcnt vmcnt(12)
	v_lshlrev_b32_e32 v244, 16, v166
	v_and_b32_e32 v245, 0xffff0000, v166
	v_lshlrev_b32_e32 v166, 16, v167
	v_and_b32_e32 v167, 0xffff0000, v167
	v_pk_mul_f32 v[106:107], v[106:107], v[166:167]
	v_pk_mul_f32 v[104:105], v[104:105], v[244:245]
	v_pk_add_f32 v[106:107], v[106:107], v[208:209]
	v_pk_add_f32 v[104:105], v[104:105], v[206:207]
	v_cvt_pk_bf16_f32 v104, v104, v105
	v_cvt_pk_bf16_f32 v105, v106, v107
	global_store_dwordx2 v[242:243], v[104:105], off offset:32
	global_load_dwordx4 v[206:209], v[238:239], off offset:64
	s_waitcnt vmcnt(13)
	v_lshlrev_b32_e32 v244, 16, v168
	v_and_b32_e32 v245, 0xffff0000, v168
	v_lshlrev_b32_e32 v168, 16, v169
	v_and_b32_e32 v169, 0xffff0000, v169
	v_pk_mul_f32 v[102:103], v[102:103], v[168:169]
	v_pk_mul_f32 v[100:101], v[100:101], v[244:245]
	v_pk_add_f32 v[102:103], v[102:103], v[212:213]
	v_pk_add_f32 v[100:101], v[100:101], v[210:211]
	v_cvt_pk_bf16_f32 v100, v100, v101
	v_cvt_pk_bf16_f32 v101, v102, v103
	global_store_dwordx2 v[242:243], v[100:101], off offset:64
	global_load_dwordx4 v[210:213], v[238:239], off offset:128
	s_waitcnt vmcnt(14)
	v_lshlrev_b32_e32 v244, 16, v170
	v_and_b32_e32 v245, 0xffff0000, v170
	v_lshlrev_b32_e32 v170, 16, v171
	v_and_b32_e32 v171, 0xffff0000, v171
	v_pk_mul_f32 v[98:99], v[98:99], v[170:171]
	v_pk_mul_f32 v[96:97], v[96:97], v[244:245]
	v_pk_add_f32 v[98:99], v[98:99], v[232:233]
	v_pk_add_f32 v[96:97], v[96:97], v[230:231]
	v_cvt_pk_bf16_f32 v96, v96, v97
	v_cvt_pk_bf16_f32 v97, v98, v99
	global_store_dwordx2 v[242:243], v[96:97], off offset:96
	global_load_dwordx4 v[230:233], v[238:239], off offset:192
	s_waitcnt vmcnt(14)
	v_lshlrev_b32_e32 v244, 16, v172
	v_and_b32_e32 v245, 0xffff0000, v172
	v_lshlrev_b32_e32 v172, 16, v173
	v_and_b32_e32 v173, 0xffff0000, v173
	v_pk_mul_f32 v[94:95], v[94:95], v[172:173]
	v_pk_mul_f32 v[92:93], v[92:93], v[244:245]
	v_pk_add_f32 v[94:95], v[94:95], v[188:189]
	v_pk_add_f32 v[92:93], v[92:93], v[186:187]
	v_lshl_add_u64 v[240:241], v[146:147], 0, s[2:3]
	v_cvt_pk_bf16_f32 v92, v92, v93
	v_cvt_pk_bf16_f32 v93, v94, v95
	global_store_dwordx2 v[240:241], v[92:93], off
	s_waitcnt vmcnt(13)
; DI unsigned pack2(float a, float b) { return (unsigned)f2bf(a) | ((unsigned)f2bf(b) << 16); }
; DI float bflo(unsigned w) { return __uint_as_float(w << 16); }
; DI float bfhi(unsigned w) { return __uint_as_float(w & 0xffff0000u); }
;   DI void operator()(f32x4 (&acc)[4][4], int m0w, int n0w, int fr, int fq) const {
; #pragma unroll
;     for (int mi = 0; mi < 4; ++mi)
; #pragma unroll
;       for (int ni = 0; ni < 4; ++ni) {
;         const size_t o = (size_t)(m0w + mi * 16 + fr) * D + n0w + ni * 16 + fq * 4;
;         const uint2 gw = *(const uint2*)(G + o);
;         f32x4 m;
;         m[0] = bflo(gw.x) * acc[mi][ni][0]; m[1] = bfhi(gw.x) * acc[mi][ni][1];
;         m[2] = bflo(gw.y) * acc[mi][ni][2]; m[3] = bfhi(gw.y) * acc[mi][ni][3];
;         if (b > 0) m += *(const f32x4*)(MACC + o);
;         if (b < 2) *(f32x4*)(MACC + o) = m;
;         else { uint2 w; w.x = pack2(m[0], m[1]); w.y = pack2(m[2], m[3]); *(uint2*)(MERGED + o) = w; }
;       }
;   }
	v_lshlrev_b32_e32 v244, 16, v174
	v_and_b32_e32 v245, 0xffff0000, v174
	v_lshlrev_b32_e32 v174, 16, v175
	v_and_b32_e32 v175, 0xffff0000, v175
	v_pk_mul_f32 v[90:91], v[90:91], v[174:175]
	v_pk_mul_f32 v[88:89], v[88:89], v[244:245]
	v_pk_add_f32 v[90:91], v[90:91], v[192:193]
	v_pk_add_f32 v[88:89], v[88:89], v[190:191]
	v_cvt_pk_bf16_f32 v88, v88, v89
	v_cvt_pk_bf16_f32 v89, v90, v91
	global_store_dwordx2 v[240:241], v[88:89], off offset:32
	s_waitcnt vmcnt(12)
	v_lshlrev_b32_e32 v244, 16, v176
	v_and_b32_e32 v245, 0xffff0000, v176
	v_lshlrev_b32_e32 v176, 16, v177
	v_and_b32_e32 v177, 0xffff0000, v177
	v_pk_mul_f32 v[86:87], v[86:87], v[176:177]
	v_pk_mul_f32 v[84:85], v[84:85], v[244:245]
	v_pk_add_f32 v[86:87], v[86:87], v[196:197]
	v_pk_add_f32 v[84:85], v[84:85], v[194:195]
	v_cvt_pk_bf16_f32 v84, v84, v85
	v_cvt_pk_bf16_f32 v85, v86, v87
	global_store_dwordx2 v[240:241], v[84:85], off offset:64
	s_waitcnt vmcnt(11)
	v_lshlrev_b32_e32 v244, 16, v178
	v_and_b32_e32 v245, 0xffff0000, v178
	v_lshlrev_b32_e32 v178, 16, v179
	v_and_b32_e32 v179, 0xffff0000, v179
	v_pk_mul_f32 v[82:83], v[82:83], v[178:179]
	v_pk_mul_f32 v[80:81], v[80:81], v[244:245]
	v_pk_add_f32 v[82:83], v[82:83], v[200:201]
	v_pk_add_f32 v[80:81], v[80:81], v[198:199]
	v_cvt_pk_bf16_f32 v80, v80, v81
	v_cvt_pk_bf16_f32 v81, v82, v83
	global_store_dwordx2 v[240:241], v[80:81], off offset:96
	s_waitcnt vmcnt(10)
	v_lshlrev_b32_e32 v244, 16, v180
	v_and_b32_e32 v245, 0xffff0000, v180
	v_lshlrev_b32_e32 v180, 16, v181
	v_and_b32_e32 v181, 0xffff0000, v181
	v_pk_mul_f32 v[78:79], v[78:79], v[180:181]
	v_pk_mul_f32 v[76:77], v[76:77], v[244:245]
	v_pk_add_f32 v[78:79], v[78:79], v[204:205]
	v_pk_add_f32 v[76:77], v[76:77], v[202:203]
	v_lshl_add_u64 v[242:243], v[148:149], 0, s[2:3]
	v_cvt_pk_bf16_f32 v76, v76, v77
	v_cvt_pk_bf16_f32 v77, v78, v79
	global_store_dwordx2 v[242:243], v[76:77], off
	s_waitcnt vmcnt(9)
	v_lshlrev_b32_e32 v244, 16, v182
	v_and_b32_e32 v245, 0xffff0000, v182
	v_lshlrev_b32_e32 v182, 16, v183
	v_and_b32_e32 v183, 0xffff0000, v183
	v_pk_mul_f32 v[74:75], v[74:75], v[182:183]
	v_pk_mul_f32 v[72:73], v[72:73], v[244:245]
	v_pk_add_f32 v[74:75], v[74:75], v[208:209]
	v_pk_add_f32 v[72:73], v[72:73], v[206:207]
	v_cvt_pk_bf16_f32 v72, v72, v73
	v_cvt_pk_bf16_f32 v73, v74, v75
	global_store_dwordx2 v[242:243], v[72:73], off offset:32
	s_waitcnt vmcnt(8)
	v_lshlrev_b32_e32 v244, 16, v226
	v_and_b32_e32 v245, 0xffff0000, v226
	v_lshlrev_b32_e32 v226, 16, v227
	v_and_b32_e32 v227, 0xffff0000, v227
	v_pk_mul_f32 v[70:71], v[70:71], v[226:227]
	v_pk_mul_f32 v[68:69], v[68:69], v[244:245]
	v_pk_add_f32 v[70:71], v[70:71], v[212:213]
	v_pk_add_f32 v[68:69], v[68:69], v[210:211]
	v_cvt_pk_bf16_f32 v68, v68, v69
	v_cvt_pk_bf16_f32 v69, v70, v71
	global_store_dwordx2 v[242:243], v[68:69], off offset:64
	s_waitcnt vmcnt(7)
	v_lshlrev_b32_e32 v244, 16, v228
	v_and_b32_e32 v245, 0xffff0000, v228
	v_lshlrev_b32_e32 v228, 16, v229
	v_and_b32_e32 v229, 0xffff0000, v229
	v_pk_mul_f32 v[66:67], v[66:67], v[228:229]
	v_pk_mul_f32 v[64:65], v[64:65], v[244:245]
	v_pk_add_f32 v[66:67], v[66:67], v[232:233]
	v_pk_add_f32 v[64:65], v[64:65], v[230:231]
	v_cvt_pk_bf16_f32 v64, v64, v65
	v_cvt_pk_bf16_f32 v65, v66, v67
	global_store_dwordx2 v[242:243], v[64:65], off offset:96
	s_branch .LBB0_450
.Lem_n:
	s_and_b64 vcc, exec, s[24:25]
	s_cbranch_vccz .Lem_np
	s_waitcnt vmcnt(15)
	v_lshlrev_b32_e32 v244, 16, v156
	v_and_b32_e32 v245, 0xffff0000, v156
	v_lshlrev_b32_e32 v156, 16, v157
	v_and_b32_e32 v157, 0xffff0000, v157
	v_pk_mul_f32 v[126:127], v[126:127], v[156:157]
	v_pk_mul_f32 v[124:125], v[124:125], v[244:245]
	global_store_dwordx4 v[150:151], v[124:127], off
	s_waitcnt vmcnt(15)
	v_lshlrev_b32_e32 v244, 16, v158
	v_and_b32_e32 v245, 0xffff0000, v158
	v_lshlrev_b32_e32 v158, 16, v159
	v_and_b32_e32 v159, 0xffff0000, v159
	v_pk_mul_f32 v[122:123], v[122:123], v[158:159]
	v_pk_mul_f32 v[120:121], v[120:121], v[244:245]
	global_store_dwordx4 v[150:151], v[120:123], off offset:64
	s_waitcnt vmcnt(15)
	v_lshlrev_b32_e32 v244, 16, v160
	v_and_b32_e32 v245, 0xffff0000, v160
	v_lshlrev_b32_e32 v160, 16, v161
	v_and_b32_e32 v161, 0xffff0000, v161
	v_pk_mul_f32 v[118:119], v[118:119], v[160:161]
	v_pk_mul_f32 v[116:117], v[116:117], v[244:245]
	global_store_dwordx4 v[150:151], v[116:119], off offset:128
	s_waitcnt vmcnt(15)
	v_lshlrev_b32_e32 v244, 16, v162
	v_and_b32_e32 v245, 0xffff0000, v162
	v_lshlrev_b32_e32 v162, 16, v163
	v_and_b32_e32 v163, 0xffff0000, v163
	v_pk_mul_f32 v[114:115], v[114:115], v[162:163]
	v_pk_mul_f32 v[112:113], v[112:113], v[244:245]
	global_store_dwordx4 v[150:151], v[112:115], off offset:192
	s_waitcnt vmcnt(15)
	v_lshlrev_b32_e32 v244, 16, v164
	v_and_b32_e32 v245, 0xffff0000, v164
	v_lshlrev_b32_e32 v164, 16, v165
	v_and_b32_e32 v165, 0xffff0000, v165
	v_pk_mul_f32 v[110:111], v[110:111], v[164:165]
	v_pk_mul_f32 v[108:109], v[108:109], v[244:245]
	global_store_dwordx4 v[152:153], v[108:111], off
	s_waitcnt vmcnt(15)
	v_lshlrev_b32_e32 v244, 16, v166
	v_and_b32_e32 v245, 0xffff0000, v166
	v_lshlrev_b32_e32 v166, 16, v167
	v_and_b32_e32 v167, 0xffff0000, v167
	v_pk_mul_f32 v[106:107], v[106:107], v[166:167]
	v_pk_mul_f32 v[104:105], v[104:105], v[244:245]
	global_store_dwordx4 v[152:153], v[104:107], off offset:64
	s_waitcnt vmcnt(15)
	v_lshlrev_b32_e32 v244, 16, v168
	v_and_b32_e32 v245, 0xffff0000, v168
	v_lshlrev_b32_e32 v168, 16, v169
	v_and_b32_e32 v169, 0xffff0000, v169
	v_pk_mul_f32 v[102:103], v[102:103], v[168:169]
	v_pk_mul_f32 v[100:101], v[100:101], v[244:245]
	global_store_dwordx4 v[152:153], v[100:103], off offset:128
	s_waitcnt vmcnt(15)
; DI unsigned pack2(float a, float b) { return (unsigned)f2bf(a) | ((unsigned)f2bf(b) << 16); }
; DI float bflo(unsigned w) { return __uint_as_float(w << 16); }
; DI float bfhi(unsigned w) { return __uint_as_float(w & 0xffff0000u); }
;   DI void operator()(f32x4 (&acc)[4][4], int m0w, int n0w, int fr, int fq) const {
; #pragma unroll
;     for (int mi = 0; mi < 4; ++mi)
; #pragma unroll
;       for (int ni = 0; ni < 4; ++ni) {
;         const size_t o = (size_t)(m0w + mi * 16 + fr) * D + n0w + ni * 16 + fq * 4;
;         const uint2 gw = *(const uint2*)(G + o);
;         f32x4 m;
;         m[0] = bflo(gw.x) * acc[mi][ni][0]; m[1] = bfhi(gw.x) * acc[mi][ni][1];
;         m[2] = bflo(gw.y) * acc[mi][ni][2]; m[3] = bfhi(gw.y) * acc[mi][ni][3];
;         if (b > 0) m += *(const f32x4*)(MACC + o);
;         if (b < 2) *(f32x4*)(MACC + o) = m;
;         else { uint2 w; w.x = pack2(m[0], m[1]); w.y = pack2(m[2], m[3]); *(uint2*)(MERGED + o) = w; }
;       }
;   }
	v_lshlrev_b32_e32 v244, 16, v170
	v_and_b32_e32 v245, 0xffff0000, v170
	v_lshlrev_b32_e32 v170, 16, v171
	v_and_b32_e32 v171, 0xffff0000, v171
	v_pk_mul_f32 v[98:99], v[98:99], v[170:171]
	v_pk_mul_f32 v[96:97], v[96:97], v[244:245]
	global_store_dwordx4 v[152:153], v[96:99], off offset:192
	s_waitcnt vmcnt(15)
	v_lshlrev_b32_e32 v244, 16, v172
	v_and_b32_e32 v245, 0xffff0000, v172
	v_lshlrev_b32_e32 v172, 16, v173
	v_and_b32_e32 v173, 0xffff0000, v173
	v_pk_mul_f32 v[94:95], v[94:95], v[172:173]
	v_pk_mul_f32 v[92:93], v[92:93], v[244:245]
	global_store_dwordx4 v[236:237], v[92:95], off
	s_waitcnt vmcnt(15)
	v_lshlrev_b32_e32 v244, 16, v174
	v_and_b32_e32 v245, 0xffff0000, v174
	v_lshlrev_b32_e32 v174, 16, v175
	v_and_b32_e32 v175, 0xffff0000, v175
	v_pk_mul_f32 v[90:91], v[90:91], v[174:175]
	v_pk_mul_f32 v[88:89], v[88:89], v[244:245]
	global_store_dwordx4 v[236:237], v[88:91], off offset:64
	s_waitcnt vmcnt(15)
	v_lshlrev_b32_e32 v244, 16, v176
	v_and_b32_e32 v245, 0xffff0000, v176
	v_lshlrev_b32_e32 v176, 16, v177
	v_and_b32_e32 v177, 0xffff0000, v177
	v_pk_mul_f32 v[86:87], v[86:87], v[176:177]
	v_pk_mul_f32 v[84:85], v[84:85], v[244:245]
	global_store_dwordx4 v[236:237], v[84:87], off offset:128
	s_waitcnt vmcnt(15)
	v_lshlrev_b32_e32 v244, 16, v178
	v_and_b32_e32 v245, 0xffff0000, v178
	v_lshlrev_b32_e32 v178, 16, v179
	v_and_b32_e32 v179, 0xffff0000, v179
	v_pk_mul_f32 v[82:83], v[82:83], v[178:179]
	v_pk_mul_f32 v[80:81], v[80:81], v[244:245]
	global_store_dwordx4 v[236:237], v[80:83], off offset:192
	s_waitcnt vmcnt(15)
	v_lshlrev_b32_e32 v244, 16, v180
	v_and_b32_e32 v245, 0xffff0000, v180
	v_lshlrev_b32_e32 v180, 16, v181
	v_and_b32_e32 v181, 0xffff0000, v181
	v_pk_mul_f32 v[78:79], v[78:79], v[180:181]
	v_pk_mul_f32 v[76:77], v[76:77], v[244:245]
	global_store_dwordx4 v[238:239], v[76:79], off
	s_waitcnt vmcnt(15)
	v_lshlrev_b32_e32 v244, 16, v182
	v_and_b32_e32 v245, 0xffff0000, v182
	v_lshlrev_b32_e32 v182, 16, v183
	v_and_b32_e32 v183, 0xffff0000, v183
	v_pk_mul_f32 v[74:75], v[74:75], v[182:183]
	v_pk_mul_f32 v[72:73], v[72:73], v[244:245]
	global_store_dwordx4 v[238:239], v[72:75], off offset:64
	s_waitcnt vmcnt(15)
	v_lshlrev_b32_e32 v244, 16, v226
	v_and_b32_e32 v245, 0xffff0000, v226
	v_lshlrev_b32_e32 v226, 16, v227
	v_and_b32_e32 v227, 0xffff0000, v227
	v_pk_mul_f32 v[70:71], v[70:71], v[226:227]
	v_pk_mul_f32 v[68:69], v[68:69], v[244:245]
	global_store_dwordx4 v[238:239], v[68:71], off offset:128
	s_waitcnt vmcnt(15)
	v_lshlrev_b32_e32 v244, 16, v228
	v_and_b32_e32 v245, 0xffff0000, v228
	v_lshlrev_b32_e32 v228, 16, v229
	v_and_b32_e32 v229, 0xffff0000, v229
	v_pk_mul_f32 v[66:67], v[66:67], v[228:229]
	v_pk_mul_f32 v[64:65], v[64:65], v[244:245]
	global_store_dwordx4 v[238:239], v[64:67], off offset:192
	s_branch .LBB0_450
; DI unsigned pack2(float a, float b) { return (unsigned)f2bf(a) | ((unsigned)f2bf(b) << 16); }
; DI float bflo(unsigned w) { return __uint_as_float(w << 16); }
; DI float bfhi(unsigned w) { return __uint_as_float(w & 0xffff0000u); }
;   DI void operator()(f32x4 (&acc)[4][4], int m0w, int n0w, int fr, int fq) const {
; #pragma unroll
;     for (int mi = 0; mi < 4; ++mi)
; #pragma unroll
;       for (int ni = 0; ni < 4; ++ni) {
;         const size_t o = (size_t)(m0w + mi * 16 + fr) * D + n0w + ni * 16 + fq * 4;
;         const uint2 gw = *(const uint2*)(G + o);
;         f32x4 m;
;         m[0] = bflo(gw.x) * acc[mi][ni][0]; m[1] = bfhi(gw.x) * acc[mi][ni][1];
;         m[2] = bflo(gw.y) * acc[mi][ni][2]; m[3] = bfhi(gw.y) * acc[mi][ni][3];
;         if (b > 0) m += *(const f32x4*)(MACC + o);
;         if (b < 2) *(f32x4*)(MACC + o) = m;
;         else { uint2 w; w.x = pack2(m[0], m[1]); w.y = pack2(m[2], m[3]); *(uint2*)(MERGED + o) = w; }
;       }
;   }
.Lem_np:
	s_waitcnt vmcnt(15)
	v_lshlrev_b32_e32 v244, 16, v156
	v_and_b32_e32 v245, 0xffff0000, v156
	v_lshlrev_b32_e32 v156, 16, v157
	v_and_b32_e32 v157, 0xffff0000, v157
	v_pk_mul_f32 v[126:127], v[126:127], v[156:157]
	v_pk_mul_f32 v[124:125], v[124:125], v[244:245]
	v_lshl_add_u64 v[240:241], v[140:141], 0, s[2:3]
	v_cvt_pk_bf16_f32 v124, v124, v125
	v_cvt_pk_bf16_f32 v125, v126, v127
	global_store_dwordx2 v[240:241], v[124:125], off
	s_waitcnt vmcnt(15)
	v_lshlrev_b32_e32 v244, 16, v158
	v_and_b32_e32 v245, 0xffff0000, v158
	v_lshlrev_b32_e32 v158, 16, v159
	v_and_b32_e32 v159, 0xffff0000, v159
	v_pk_mul_f32 v[122:123], v[122:123], v[158:159]
	v_pk_mul_f32 v[120:121], v[120:121], v[244:245]
	v_cvt_pk_bf16_f32 v120, v120, v121
	v_cvt_pk_bf16_f32 v121, v122, v123
	global_store_dwordx2 v[240:241], v[120:121], off offset:32
	s_waitcnt vmcnt(15)
	v_lshlrev_b32_e32 v244, 16, v160
	v_and_b32_e32 v245, 0xffff0000, v160
	v_lshlrev_b32_e32 v160, 16, v161
	v_and_b32_e32 v161, 0xffff0000, v161
	v_pk_mul_f32 v[118:119], v[118:119], v[160:161]
	v_pk_mul_f32 v[116:117], v[116:117], v[244:245]
	v_cvt_pk_bf16_f32 v116, v116, v117
	v_cvt_pk_bf16_f32 v117, v118, v119
	global_store_dwordx2 v[240:241], v[116:117], off offset:64
	s_waitcnt vmcnt(15)
	v_lshlrev_b32_e32 v244, 16, v162
	v_and_b32_e32 v245, 0xffff0000, v162
	v_lshlrev_b32_e32 v162, 16, v163
	v_and_b32_e32 v163, 0xffff0000, v163
	v_pk_mul_f32 v[114:115], v[114:115], v[162:163]
	v_pk_mul_f32 v[112:113], v[112:113], v[244:245]
	v_cvt_pk_bf16_f32 v112, v112, v113
	v_cvt_pk_bf16_f32 v113, v114, v115
	global_store_dwordx2 v[240:241], v[112:113], off offset:96
	s_waitcnt vmcnt(15)
	v_lshlrev_b32_e32 v244, 16, v164
	v_and_b32_e32 v245, 0xffff0000, v164
	v_lshlrev_b32_e32 v164, 16, v165
	v_and_b32_e32 v165, 0xffff0000, v165
	v_pk_mul_f32 v[110:111], v[110:111], v[164:165]
	v_pk_mul_f32 v[108:109], v[108:109], v[244:245]
	v_lshl_add_u64 v[242:243], v[142:143], 0, s[2:3]
	v_cvt_pk_bf16_f32 v108, v108, v109
	v_cvt_pk_bf16_f32 v109, v110, v111
	global_store_dwordx2 v[242:243], v[108:109], off
	s_waitcnt vmcnt(15)
	v_lshlrev_b32_e32 v244, 16, v166
	v_and_b32_e32 v245, 0xffff0000, v166
	v_lshlrev_b32_e32 v166, 16, v167
	v_and_b32_e32 v167, 0xffff0000, v167
	v_pk_mul_f32 v[106:107], v[106:107], v[166:167]
	v_pk_mul_f32 v[104:105], v[104:105], v[244:245]
	v_cvt_pk_bf16_f32 v104, v104, v105
	v_cvt_pk_bf16_f32 v105, v106, v107
	global_store_dwordx2 v[242:243], v[104:105], off offset:32
	s_waitcnt vmcnt(15)
	v_lshlrev_b32_e32 v244, 16, v168
	v_and_b32_e32 v245, 0xffff0000, v168
	v_lshlrev_b32_e32 v168, 16, v169
	v_and_b32_e32 v169, 0xffff0000, v169
	v_pk_mul_f32 v[102:103], v[102:103], v[168:169]
	v_pk_mul_f32 v[100:101], v[100:101], v[244:245]
	v_cvt_pk_bf16_f32 v100, v100, v101
	v_cvt_pk_bf16_f32 v101, v102, v103
	global_store_dwordx2 v[242:243], v[100:101], off offset:64
	s_waitcnt vmcnt(15)
	v_lshlrev_b32_e32 v244, 16, v170
	v_and_b32_e32 v245, 0xffff0000, v170
	v_lshlrev_b32_e32 v170, 16, v171
	v_and_b32_e32 v171, 0xffff0000, v171
	v_pk_mul_f32 v[98:99], v[98:99], v[170:171]
	v_pk_mul_f32 v[96:97], v[96:97], v[244:245]
	v_cvt_pk_bf16_f32 v96, v96, v97
	v_cvt_pk_bf16_f32 v97, v98, v99
	global_store_dwordx2 v[242:243], v[96:97], off offset:96
	s_waitcnt vmcnt(15)
	v_lshlrev_b32_e32 v244, 16, v172
	v_and_b32_e32 v245, 0xffff0000, v172
	v_lshlrev_b32_e32 v172, 16, v173
	v_and_b32_e32 v173, 0xffff0000, v173
	v_pk_mul_f32 v[94:95], v[94:95], v[172:173]
	v_pk_mul_f32 v[92:93], v[92:93], v[244:245]
	v_lshl_add_u64 v[240:241], v[146:147], 0, s[2:3]
	v_cvt_pk_bf16_f32 v92, v92, v93
	v_cvt_pk_bf16_f32 v93, v94, v95
	global_store_dwordx2 v[240:241], v[92:93], off
	s_waitcnt vmcnt(15)
	v_lshlrev_b32_e32 v244, 16, v174
	v_and_b32_e32 v245, 0xffff0000, v174
	v_lshlrev_b32_e32 v174, 16, v175
	v_and_b32_e32 v175, 0xffff0000, v175
	v_pk_mul_f32 v[90:91], v[90:91], v[174:175]
	v_pk_mul_f32 v[88:89], v[88:89], v[244:245]
	v_cvt_pk_bf16_f32 v88, v88, v89
	v_cvt_pk_bf16_f32 v89, v90, v91
	global_store_dwordx2 v[240:241], v[88:89], off offset:32
	s_waitcnt vmcnt(15)
	v_lshlrev_b32_e32 v244, 16, v176
	v_and_b32_e32 v245, 0xffff0000, v176
	v_lshlrev_b32_e32 v176, 16, v177
	v_and_b32_e32 v177, 0xffff0000, v177
	v_pk_mul_f32 v[86:87], v[86:87], v[176:177]
	v_pk_mul_f32 v[84:85], v[84:85], v[244:245]
	v_cvt_pk_bf16_f32 v84, v84, v85
	v_cvt_pk_bf16_f32 v85, v86, v87
	global_store_dwordx2 v[240:241], v[84:85], off offset:64
	s_waitcnt vmcnt(15)
	v_lshlrev_b32_e32 v244, 16, v178
	v_and_b32_e32 v245, 0xffff0000, v178
	v_lshlrev_b32_e32 v178, 16, v179
	v_and_b32_e32 v179, 0xffff0000, v179
	v_pk_mul_f32 v[82:83], v[82:83], v[178:179]
	v_pk_mul_f32 v[80:81], v[80:81], v[244:245]
	v_cvt_pk_bf16_f32 v80, v80, v81
	v_cvt_pk_bf16_f32 v81, v82, v83
	global_store_dwordx2 v[240:241], v[80:81], off offset:96
	s_waitcnt vmcnt(15)
	v_lshlrev_b32_e32 v244, 16, v180
	v_and_b32_e32 v245, 0xffff0000, v180
	v_lshlrev_b32_e32 v180, 16, v181
	v_and_b32_e32 v181, 0xffff0000, v181
	v_pk_mul_f32 v[78:79], v[78:79], v[180:181]
	v_pk_mul_f32 v[76:77], v[76:77], v[244:245]
	v_lshl_add_u64 v[242:243], v[148:149], 0, s[2:3]
	v_cvt_pk_bf16_f32 v76, v76, v77
	v_cvt_pk_bf16_f32 v77, v78, v79
	global_store_dwordx2 v[242:243], v[76:77], off
	s_waitcnt vmcnt(15)
	v_lshlrev_b32_e32 v244, 16, v182
	v_and_b32_e32 v245, 0xffff0000, v182
	v_lshlrev_b32_e32 v182, 16, v183
	v_and_b32_e32 v183, 0xffff0000, v183
	v_pk_mul_f32 v[74:75], v[74:75], v[182:183]
	v_pk_mul_f32 v[72:73], v[72:73], v[244:245]
	v_cvt_pk_bf16_f32 v72, v72, v73
	v_cvt_pk_bf16_f32 v73, v74, v75
	global_store_dwordx2 v[242:243], v[72:73], off offset:32
	s_waitcnt vmcnt(15)
	v_lshlrev_b32_e32 v244, 16, v226
	v_and_b32_e32 v245, 0xffff0000, v226
	v_lshlrev_b32_e32 v226, 16, v227
	v_and_b32_e32 v227, 0xffff0000, v227
	v_pk_mul_f32 v[70:71], v[70:71], v[226:227]
	v_pk_mul_f32 v[68:69], v[68:69], v[244:245]
	v_cvt_pk_bf16_f32 v68, v68, v69
	v_cvt_pk_bf16_f32 v69, v70, v71
	global_store_dwordx2 v[242:243], v[68:69], off offset:64
	s_waitcnt vmcnt(15)
	v_lshlrev_b32_e32 v244, 16, v228
	v_and_b32_e32 v245, 0xffff0000, v228
	v_lshlrev_b32_e32 v228, 16, v229
	v_and_b32_e32 v229, 0xffff0000, v229
	v_pk_mul_f32 v[66:67], v[66:67], v[228:229]
	v_pk_mul_f32 v[64:65], v[64:65], v[244:245]
	v_cvt_pk_bf16_f32 v64, v64, v65
	v_cvt_pk_bf16_f32 v65, v66, v67
	global_store_dwordx2 v[242:243], v[64:65], off offset:96
	s_branch .LBB0_450
